# v15 + attention: next unit's Q fragments prefetched during the current unit's epilogue
# baseline (speedup 1.0000x reference)
; #define ATT_LAS __attribute__((address_space(3)))
; #define DMA_T(t, s) do { const long go_ = (long)(t) * KVBLK * PITCH; const unsigned sd_ = (unsigned)__builtin_amdgcn_readfirstlane(pdst + (s) * SLOTB); \
;         glds16(ksrc + go_, sd_); glds16(ksrc + go_ + 64, sd_ + OFF_K1); glds16(vsrc + go_, sd_ + OFF_V); glds16(vsrc + go_ + 64, sd_ + OFF_V + 8192); } while (0)
; __device__ __forceinline__ void attn_unit(const int b, const int h, const int qb, const bf16_t* Q, const bf16_t* K, const bf16_t* V, bf16_t* O, ATT_LAS char* shm, const float lam) {
;     const int tid = threadIdx.x, lane = tid & 63, r32 = lane & 31, hi = lane >> 5; const int wid = __builtin_amdgcn_readfirstlane(tid >> 6), sub = wid >> 2, w4 = wid & 3;
;     const long rowbase = (long)b * SEQ; const int q0 = qb * QB2;
;     const bf16_t* Qw = Q + (rowbase + q0 + w4 * QBLK) * PITCH + h * 128 + sub * 64;
;     const bf16_t* Kh = K + rowbase * PITCH + h * 128; const bf16_t* Vh = V + rowbase * PITCH + h * 128;
;     const unsigned lds0 = (unsigned)(uintptr_t)shm;
;     const bf16_t* ksrc = Kh + (long)lane * PITCH + wid * 8;
;     const bf16_t* vsrc = Vh + (long)(16 * (wid & 3) + (lane >> 2)) * PITCH + (wid >> 2) * 32 + (lane & 3) * 8;
;     const unsigned pdst = lds0 + wid * 1024;
;     ...
;     const lds_cptr kp0 = (lds_cptr)shm + sub * OFF_K1 + hi * 1024 + r32 * 16;
;     const lds_cptr vp0 = (lds_cptr)shm + OFF_V + ((lane >> 4) & 1) * 32 + (lane & 3) * 8 + (4 * hi + ((lane & 15) >> 2)) * 64;
;     const int NT = (q0 + QB2) / KVBLK;
;     const int mylast = q0 / KVBLK + (w4 >> 1);
;     DMA_T(0, 0); DMA_T(1, 1);
;     bf16x8 qr[4];
; #pragma unroll
;     for (int d0 = 0; d0 < 4; ++d0) qr[d0] = *reinterpret_cast<const bf16x8*>(&Qw[(long)r32 * PITCH + d0 * 16 + hi * 8]);
;     asm volatile("" : "+v"(qr[0]), "+v"(qr[1]), "+v"(qr[2]), "+v"(qr[3]));
;     f32x16 o[4]; o[0] = f32x16{}; o[1] = f32x16{}; o[2] = f32x16{}; o[3] = f32x16{};
;     float l_reg = 0.f;
;     int slot = 0, slot2 = 2;
.LBB0_466:
	s_bitcmp0_b32 s34, 0
	v_readfirstlane_b32 s3, v164
	s_cselect_b32 s44, s6, s7
	s_bfe_u32 s31, s3, 0x20006
	s_lshl_b32 s30, s31, 14
	s_lshl_b32 s16, s44, 16
	s_or_b32 s16, s30, s16
	s_or_b32 s26, s0, s16
	s_mov_b32 s27, s1
	s_lshr_b32 s45, s3, 6
	s_lshr_b32 s39, s3, 8
	s_lshl_b32 s46, s44, 7
	s_lshl_b64 s[26:27], s[26:27], 1
	s_add_u32 s36, s85, s26
	s_addc_u32 s37, s86, s27
	s_lshl_b32 s35, s34, 7
	s_lshl_b32 s16, s34, 8
	s_add_u32 s38, s36, s16
	s_addc_u32 s41, s37, 0
	s_lshl_b32 s36, s39, 6
	s_lshl_b32 s40, s39, 7
	s_add_u32 s40, s38, s40
	s_addc_u32 s41, s41, 0
	s_add_u32 s42, s8, s16
	s_addc_u32 s43, s9, 0
	s_lshl_b32 s38, s31, 13
	v_or_b32_e32 v0, s38, v152
	v_lshl_add_u64 v[2:3], v[114:115], 0, s[16:17]
	s_lshl_b32 s16, s45, 13
	v_lshlrev_b32_e32 v0, 1, v0
	s_lshl_b32 s31, s45, 10
	s_mov_b32 s37, s17
	v_lshl_add_u64 v[2:3], v[2:3], 0, s[16:17]
	v_lshl_add_u64 v[4:5], s[42:43], 0, v[0:1]
	s_add_i32 s31, s31, 0
	s_mov_b32 s16, m0
	s_mov_b32 m0, s31
	s_nop 0
	global_load_lds_dwordx4 v[2:3], off
	s_mov_b32 m0, s16
	v_lshl_add_u64 v[4:5], v[4:5], 0, s[36:37]
	v_mov_b32_e32 v121, v1
	v_lshl_add_u64 v[6:7], v[2:3], 0, s[18:19]
	s_add_i32 s16, s31, 0x2000
	s_mov_b32 s42, m0
	s_mov_b32 m0, s16
	s_nop 0
	global_load_lds_dwordx4 v[6:7], off
	s_mov_b32 m0, s42
	v_lshl_add_u64 v[4:5], v[4:5], 0, v[120:121]
	s_add_i32 s16, s31, 0x4000
	s_mov_b32 s42, m0
	s_mov_b32 m0, s16
	s_nop 0
	global_load_lds_dwordx4 v[4:5], off
	s_mov_b32 m0, s42
	v_lshl_add_u64 v[6:7], v[4:5], 0, s[18:19]
	s_add_i32 s16, s31, 0x6000
	s_mov_b32 s42, m0
	s_mov_b32 m0, s16
	s_nop 0
	global_load_lds_dwordx4 v[6:7], off
	s_mov_b32 m0, s42
	s_add_i32 s16, s31, 0x8000
	v_lshl_add_u64 v[6:7], v[2:3], 0, s[20:21]
	s_mov_b32 s42, m0
	s_mov_b32 m0, s16
	s_nop 0
	global_load_lds_dwordx4 v[6:7], off
	s_mov_b32 m0, s42
	v_lshl_add_u64 v[2:3], v[2:3], 0, s[22:23]
	s_add_i32 s16, s31, 0xa000
	s_mov_b32 s42, m0
	s_mov_b32 m0, s16
	s_nop 0
	global_load_lds_dwordx4 v[2:3], off
	s_mov_b32 m0, s42
	v_lshl_add_u64 v[2:3], v[4:5], 0, s[20:21]
	s_add_i32 s16, s31, 0xc000
	s_mov_b32 s42, m0
	s_mov_b32 m0, s16
	s_nop 0
	global_load_lds_dwordx4 v[2:3], off
	s_mov_b32 m0, s42
	v_lshl_add_u64 v[2:3], v[4:5], 0, s[22:23]
	s_add_i32 s16, s31, 0xe000
	s_mov_b32 s42, m0
	s_mov_b32 m0, s16
	s_nop 0
	global_load_lds_dwordx4 v[2:3], off
	s_mov_b32 m0, s42
	s_cmp_eq_u32 s34, 0
	s_cbranch_scc1 .Lqpf_load
	v_mov_b64_e32 v[98:99], v[216:217]
	v_mov_b64_e32 v[100:101], v[218:219]
	v_mov_b64_e32 v[102:103], v[220:221]
	v_mov_b64_e32 v[104:105], v[222:223]
	v_mov_b64_e32 v[106:107], v[224:225]
	v_mov_b64_e32 v[108:109], v[226:227]
	v_mov_b64_e32 v[110:111], v[228:229]
	v_mov_b64_e32 v[112:113], v[230:231]
	s_branch .Lqpf_done
.Lqpf_load:
	global_load_dwordx4 v[98:101], v213, s[40:41] offset:96 nt
	global_load_dwordx4 v[102:105], v213, s[40:41] offset:64 nt
	global_load_dwordx4 v[106:109], v213, s[40:41] offset:32 nt
	global_load_dwordx4 v[110:113], v213, s[40:41] nt
.Lqpf_done:
	v_mov_b32_e32 v14, v1
	v_mov_b32_e32 v15, v1
	v_mov_b32_e32 v2, v1
	v_mov_b32_e32 v3, v1
	v_mov_b32_e32 v4, v1
	v_mov_b32_e32 v5, v1
	v_mov_b32_e32 v6, v1
	v_mov_b32_e32 v7, v1
	v_mov_b32_e32 v8, v1
	v_mov_b32_e32 v9, v1
	v_mov_b32_e32 v10, v1
	v_mov_b32_e32 v11, v1
	v_mov_b32_e32 v12, v1
	v_mov_b32_e32 v13, v1
	s_addk_i32 s46, 0x80
	s_bfe_u32 s16, s45, 0x10001
	s_lshl_b32 s42, s44, 1
	s_lshr_b32 s44, s3, 2
	v_lshl_add_u64 v[16:17], s[36:37], 0, v[0:1]
	v_mov_b32_e32 v0, v1
	v_mov_b64_e32 v[64:65], v[14:15]
	v_mov_b64_e32 v[48:49], v[14:15]
	v_mov_b64_e32 v[32:33], v[14:15]
	s_lshr_b32 s43, s46, 6
	s_or_b32 s42, s16, s42
	s_lshr_b32 s16, s3, 6
	s_lshl_b32 s16, s16, 13
	v_lshl_add_u64 v[142:143], v[118:119], 0, v[16:17]
	v_mov_b64_e32 v[62:63], v[12:13]
	v_mov_b64_e32 v[60:61], v[10:11]
	v_mov_b64_e32 v[58:59], v[8:9]
	v_mov_b64_e32 v[56:57], v[6:7]
	v_mov_b64_e32 v[54:55], v[4:5]
	v_mov_b64_e32 v[52:53], v[2:3]
	v_mov_b64_e32 v[50:51], v[0:1]
	v_mov_b64_e32 v[46:47], v[12:13]
	v_mov_b64_e32 v[44:45], v[10:11]
	v_mov_b64_e32 v[42:43], v[8:9]
	v_mov_b64_e32 v[40:41], v[6:7]
	v_mov_b64_e32 v[38:39], v[4:5]
	v_mov_b64_e32 v[36:37], v[2:3]
	v_mov_b64_e32 v[34:35], v[0:1]
	v_mov_b64_e32 v[30:31], v[12:13]
	v_mov_b64_e32 v[28:29], v[10:11]
	v_mov_b64_e32 v[26:27], v[8:9]
	v_mov_b64_e32 v[24:25], v[6:7]
	v_mov_b64_e32 v[22:23], v[4:5]
	v_mov_b64_e32 v[20:21], v[2:3]
	v_mov_b64_e32 v[18:19], v[0:1]
	v_mov_b64_e32 v[16:17], v[14:15]
	v_mov_b32_e32 v121, 0
	s_mov_b32 s40, 0
	s_mov_b32 s41, 2
	v_lshl_add_u32 v123, s39, 13, v154
	s_add_i32 s44, s43, -2
	s_add_i32 s45, s43, -1
	v_lshl_add_u64 v[140:141], v[116:117], 0, s[16:17]
	v_mov_b64_e32 v[14:15], v[12:13]
	v_mov_b64_e32 v[12:13], v[10:11]
	v_mov_b64_e32 v[10:11], v[8:9]
	v_mov_b64_e32 v[8:9], v[6:7]
	v_mov_b64_e32 v[6:7], v[4:5]
	v_mov_b64_e32 v[4:5], v[2:3]
	v_mov_b64_e32 v[2:3], v[0:1]
	s_mov_b32 s16, 0
	s_waitcnt vmcnt(0)
	v_and_b32_e32 v0, 63, v164
	v_and_b32_e32 v125, 31, v0
	v_lshlrev_b32_e32 v123, 7, v125
	v_lshl_add_u32 v123, s39, 13, v123
	v_lshrrev_b32_e32 v125, 5, v0
	v_bfe_u32 v162, v0, 1, 1
	v_xor_b32_e32 v125, v125, v162
	v_lshl_add_u32 v123, v125, 4, v123
	v_bfe_u32 v125, v0, 2, 2
	v_lshl_add_u32 v123, v125, 5, v123
	s_cmp_lt_u32 s43, 3
	s_cbranch_scc1 .Latt_nok2
	s_add_i32 s46, s31, 0x10000
	s_mov_b32 m0, s46
	v_lshl_add_u64 v[162:163], v[140:141], 0, s[18:19]
	global_load_lds_dwordx4 v[140:141], off
	s_add_i32 m0, s46, 0x2000
	s_nop 0
	global_load_lds_dwordx4 v[162:163], off
	v_lshl_add_u64 v[140:141], v[140:141], 0, s[20:21]

; #define ATT_LAS __attribute__((address_space(3)))
; __device__ __forceinline__ int crow(int r, int hi) { return (r & 3) + 8 * (r >> 2) + 4 * hi; }
; __device__ __forceinline__ void attn_unit(const int b, const int h, const int qb, const bf16_t* Q, const bf16_t* K, const bf16_t* V, bf16_t* O, ATT_LAS char* shm, const float lam) {
;     ...
;     { auto rr = __builtin_amdgcn_permlane32_swap(__float_as_uint(l_reg), __float_as_uint(l_reg), false, false); l_reg = __uint_as_float(rr[0]) + __uint_as_float(rr[1]); }
;     const float rl = __builtin_amdgcn_rcpf(l_reg);
;     asm volatile("s_waitcnt vmcnt(0) lgkmcnt(0)\n\ts_barrier" ::: "memory");
;     ATT_LAS float* xa = (ATT_LAS float*)shm + w4 * 4096 + lane;
;     if (sub == 0) {
; #pragma unroll
;         for (int r = 0; r < 16; ++r) { const float rli = __shfl(rl, crow(r, hi));
; #pragma unroll
;             for (int d0 = 0; d0 < 4; ++d0) xa[(d0 * 16 + r) * 64] = o[d0][r] * rli; }
.LBB0_474:
	v_mov_b32_e32 v0, v121
	s_nop 1
	v_permlane32_swap_b32_e32 v121, v0
	v_add_f32_e32 v0, v121, v0
	v_rcp_f32_e32 v0, v0
	s_waitcnt vmcnt(0) lgkmcnt(0)
	s_barrier
	s_cmp_gt_u32 s34, 2
	s_cbranch_scc1 .Lqpf_skip
	s_add_i32 s36, s34, 1
	s_bitcmp0_b32 s36, 0
	s_cselect_b32 s37, s6, s7
	s_bfe_u32 s46, s3, 0x20006
	s_lshl_b32 s46, s46, 14
	s_lshl_b32 s37, s37, 16
	s_or_b32 s37, s46, s37
	s_or_b32 s100, s0, s37
	s_mov_b32 s101, s1
	s_lshl_b64 s[100:101], s[100:101], 1
	s_add_u32 s100, s85, s100
	s_addc_u32 s101, s86, s101
	s_lshl_b32 s36, s36, 8
	s_add_u32 s100, s100, s36
	s_addc_u32 s101, s101, 0
	s_lshr_b32 s36, s3, 8
	s_lshl_b32 s36, s36, 7
	s_add_u32 s100, s100, s36
	s_addc_u32 s101, s101, 0
	global_load_dwordx4 v[216:219], v213, s[100:101] offset:96 nt
	global_load_dwordx4 v[220:223], v213, s[100:101] offset:64 nt
	global_load_dwordx4 v[224:227], v213, s[100:101] offset:32 nt
	global_load_dwordx4 v[228:231], v213, s[100:101] nt
.Lqpf_skip:
	s_cmpk_gt_u32 s3, 0xff
	v_add_u32_e32 v80, s30, v155
	s_cbranch_scc1 .LBB0_476
	v_or_b32_e32 v67, 4, v150
	ds_bpermute_b32 v66, v150, v0
	ds_bpermute_b32 v67, v67, v0
	s_waitcnt lgkmcnt(1)
	v_mul_f32_e32 v68, v50, v66
	s_waitcnt lgkmcnt(0)
	v_mul_f32_e32 v71, v51, v67
	v_mul_f32_e32 v69, v34, v66
	ds_write2st64_b32 v80, v68, v71 offset1:1
	v_mul_f32_e32 v68, v35, v67
	v_mul_f32_e32 v70, v18, v66
	v_mul_f32_e32 v66, v2, v66
	ds_write2st64_b32 v80, v69, v68 offset0:16 offset1:17
	v_mul_f32_e32 v68, v19, v67
	v_mul_f32_e32 v67, v3, v67
	v_or_b32_e32 v69, 8, v150
	ds_write2st64_b32 v80, v66, v67 offset0:48 offset1:49
	v_or_b32_e32 v66, 12, v150
	ds_bpermute_b32 v69, v69, v0
	ds_bpermute_b32 v66, v66, v0
	ds_write2st64_b32 v80, v70, v68 offset0:32 offset1:33
	s_waitcnt lgkmcnt(2)
	v_mul_f32_e32 v67, v52, v69
	s_waitcnt lgkmcnt(1)
	v_mul_f32_e32 v71, v53, v66
	v_mul_f32_e32 v68, v36, v69
	ds_write2st64_b32 v80, v67, v71 offset0:2 offset1:3
	v_mul_f32_e32 v67, v37, v66
	v_mul_f32_e32 v70, v20, v69
	v_mul_f32_e32 v69, v4, v69
	ds_write2st64_b32 v80, v68, v67 offset0:18 offset1:19
	v_mul_f32_e32 v67, v21, v66
	v_mul_f32_e32 v66, v5, v66
	v_or_b32_e32 v68, 32, v150
	ds_write2st64_b32 v80, v69, v66 offset0:50 offset1:51
	v_or_b32_e32 v66, 36, v150
	ds_bpermute_b32 v68, v68, v0
	ds_bpermute_b32 v66, v66, v0
	ds_write2st64_b32 v80, v70, v67 offset0:34 offset1:35
	s_waitcnt lgkmcnt(2)
	v_mul_f32_e32 v67, v54, v68
	s_waitcnt lgkmcnt(1)
	v_mul_f32_e32 v71, v55, v66
	v_mul_f32_e32 v69, v38, v68
	ds_write2st64_b32 v80, v67, v71 offset0:4 offset1:5
	v_mul_f32_e32 v67, v39, v66
	v_mul_f32_e32 v70, v22, v68
	v_mul_f32_e32 v68, v6, v68
	ds_write2st64_b32 v80, v69, v67 offset0:20 offset1:21
	v_mul_f32_e32 v67, v23, v66
	v_mul_f32_e32 v66, v7, v66
	v_or_b32_e32 v69, 40, v150
	ds_write2st64_b32 v80, v68, v66 offset0:52 offset1:53
	v_or_b32_e32 v66, 44, v150
	ds_bpermute_b32 v69, v69, v0
	ds_bpermute_b32 v66, v66, v0
	ds_write2st64_b32 v80, v70, v67 offset0:36 offset1:37
	s_waitcnt lgkmcnt(2)
	v_mul_f32_e32 v67, v56, v69
	s_waitcnt lgkmcnt(1)
	v_mul_f32_e32 v71, v57, v66
	v_mul_f32_e32 v68, v40, v69
	ds_write2st64_b32 v80, v67, v71 offset0:6 offset1:7
	v_mul_f32_e32 v67, v41, v66
	v_mul_f32_e32 v70, v24, v69
	v_mul_f32_e32 v69, v8, v69
	ds_write2st64_b32 v80, v68, v67 offset0:22 offset1:23
	v_mul_f32_e32 v67, v25, v66
	v_mul_f32_e32 v66, v9, v66
	ds_bpermute_b32 v68, v157, v0
	ds_write2st64_b32 v80, v69, v66 offset0:54 offset1:55
	ds_bpermute_b32 v66, v254, v0
	ds_write2st64_b32 v80, v70, v67 offset0:38 offset1:39
	s_waitcnt lgkmcnt(3)
	v_mul_f32_e32 v67, v58, v68
	v_mul_f32_e32 v69, v42, v68
	s_waitcnt lgkmcnt(1)
	v_mul_f32_e32 v71, v59, v66
	ds_write2st64_b32 v80, v67, v71 offset0:8 offset1:9
	v_mul_f32_e32 v67, v43, v66
	v_mul_f32_e32 v70, v26, v68
	v_mul_f32_e32 v68, v10, v68
	ds_write2st64_b32 v80, v69, v67 offset0:24 offset1:25
	v_mul_f32_e32 v67, v27, v66
	v_mul_f32_e32 v66, v11, v66
	ds_bpermute_b32 v69, v215, v0
	ds_write2st64_b32 v80, v68, v66 offset0:56 offset1:57
	ds_bpermute_b32 v66, v165, v0
	ds_write2st64_b32 v80, v70, v67 offset0:40 offset1:41
	s_waitcnt lgkmcnt(3)
	v_mul_f32_e32 v67, v60, v69
	v_mul_f32_e32 v68, v44, v69
	s_waitcnt lgkmcnt(1)
	v_mul_f32_e32 v71, v61, v66
	ds_write2st64_b32 v80, v67, v71 offset0:10 offset1:11
	v_mul_f32_e32 v67, v45, v66
	v_mul_f32_e32 v70, v28, v69
	v_mul_f32_e32 v69, v12, v69
	ds_write2st64_b32 v80, v68, v67 offset0:26 offset1:27
	v_mul_f32_e32 v67, v29, v66
	v_mul_f32_e32 v66, v13, v66
	ds_bpermute_b32 v68, v170, v0
	ds_write2st64_b32 v80, v69, v66 offset0:58 offset1:59
	ds_bpermute_b32 v66, v171, v0
	ds_write2st64_b32 v80, v70, v67 offset0:42 offset1:43
	s_waitcnt lgkmcnt(3)
	v_mul_f32_e32 v67, v62, v68
	v_mul_f32_e32 v69, v46, v68
	s_waitcnt lgkmcnt(1)
	v_mul_f32_e32 v71, v63, v66
	ds_write2st64_b32 v80, v67, v71 offset0:12 offset1:13
	v_mul_f32_e32 v67, v47, v66
	v_mul_f32_e32 v70, v30, v68
	v_mul_f32_e32 v68, v14, v68
	ds_write2st64_b32 v80, v69, v67 offset0:28 offset1:29
	v_mul_f32_e32 v67, v31, v66
	v_mul_f32_e32 v66, v15, v66
	ds_bpermute_b32 v69, v172, v0
	ds_write2st64_b32 v80, v68, v66 offset0:60 offset1:61
	ds_bpermute_b32 v66, v173, v0
	ds_write2st64_b32 v80, v70, v67 offset0:44 offset1:45
	s_waitcnt lgkmcnt(3)
	v_mul_f32_e32 v67, v64, v69
	v_mul_f32_e32 v68, v48, v69
	s_waitcnt lgkmcnt(1)
	v_mul_f32_e32 v71, v65, v66
	ds_write2st64_b32 v80, v67, v71 offset0:14 offset1:15
	v_mul_f32_e32 v67, v49, v66
	v_mul_f32_e32 v70, v32, v69
	v_mul_f32_e32 v69, v16, v69
	ds_write2st64_b32 v80, v68, v67 offset0:30 offset1:31
	v_mul_f32_e32 v67, v33, v66
	v_mul_f32_e32 v66, v17, v66
	ds_write2st64_b32 v80, v70, v67 offset0:46 offset1:47
	ds_write2st64_b32 v80, v69, v66 offset0:62 offset1:63
